# P5 ACT stores non-temporal (nt): the streamed-out activations stop displacing the shared A/B tile lines in L2
# speedup vs baseline: 1.0047x; 1.0047x over previous
; __device__ __forceinline__ unsigned cvt_pk_bf16(float lo, float hi) { unsigned r; asm volatile("v_cvt_pk_bf16_f32 %0, %1, %2" : "=v"(r) : "v"(lo), "v"(hi)); return r; }
;     __device__ __forceinline__ void operator()(const f32x4 (&acc)[2][2][4][2], const Unit& u, int wr, int wc, int fr, int fq) const {
;         const int row0 = u.pm * BM + wr * 64 + fr, col0 = u.pn * HALF + wc * 32 + 8 * fq;
;         float rsv[2][4];
; #pragma unroll
;         for (int ai = 0; ai < 2; ++ai)
; #pragma unroll
;             for (int m = 0; m < 4; ++m) rsv[ai][m] = ss[row0 + ai * HALF + m * 16];
;         asm volatile("" ::: "memory");
; #pragma unroll
;         for (int ai = 0; ai < 2; ++ai)
; #pragma unroll
;             for (int m = 0; m < 4; ++m) { const int row = row0 + ai * HALF + m * 16; const float rs = __builtin_amdgcn_rsqf(rsv[ai][m] * inv_n + eps);
;                 float a[8];
; #pragma unroll
;                 for (int n = 0; n < 2; ++n)
; #pragma unroll
;                     for (int i = 0; i < 4; ++i) { const float g = acc[ai][0][m][n][i] * rs, up = acc[ai][1][m][n][i] * rs;
;                         a[n * 4 + i] = g * __builtin_amdgcn_rcpf(1.0f + __builtin_amdgcn_exp2f(-1.4426950408889634f * g)) * up; }
;                 u32x4 w; w.x = cvt_pk_bf16(a[0], a[1]); w.y = cvt_pk_bf16(a[2], a[3]); w.z = cvt_pk_bf16(a[4], a[5]); w.w = cvt_pk_bf16(a[6], a[7]);
;                 *(u32x4*)(O + (size_t)row * ldc + col0) = w; }
.Lp5_kdone:
	s_waitcnt lgkmcnt(0)
	s_nop 7
	s_nop 7
	v_mov_b32_e32 v134, v254
	v_mov_b32_e32 v135, v255
	v_mov_b32_e32 v136, v186
	v_mov_b32_e32 v137, v187
	v_and_b32_e32 v254, 63, v185
	v_and_b32_e32 v255, 15, v254
	v_lshrrev_b32_e32 v186, 4, v254
	s_lshl_b32 s40, s37, 6
	v_add_u32_e32 v255, s40, v255
	v_lshlrev_b32_e32 v128, 2, v255
	v_mul_u32_u24_e32 v129, 0x2c00, v255
	s_lshl_b32 s41, s38, 6
	v_lshl_add_u32 v129, v186, 4, v129
	v_add_u32_e32 v129, s41, v129
	v_mov_b32_e32 v130, 0x358637bd
	s_lshl_b32 s40, s17, 10
	s_add_u32 s48, s76, s40
	s_addc_u32 s49, s77, 0
	s_mul_i32 s40, s17, 0x2c0000
	s_lshl_b32 s41, s18, 8
	s_add_u32 s40, s40, s41
	s_add_u32 s50, s76, 0xa800000
	s_addc_u32 s51, s77, 0
	s_add_u32 s50, s50, s40
	s_addc_u32 s51, s51, 0
	global_load_dword v138, v128, s[48:49] offset:512
	global_load_dword v139, v128, s[48:49] offset:576
	global_load_dword v140, v128, s[48:49] offset:640
	global_load_dword v141, v128, s[48:49] offset:704
	v_fmamk_f32 v131, v134, 0x3a000000, v130
	v_add_u32_e32 v132, 0x0, v129
	v_rsq_f32_e32 v131, v131
	s_nop 0
	v_mul_f32_e32 v133, 0xbfb8aa3b, v131
	v_mul_f32_e32 v131, v131, v131
	v_mul_f32_e32 v144, v133, v0
	v_mul_f32_e32 v145, v133, v1
	v_mul_f32_e32 v146, v133, v2
	v_mul_f32_e32 v147, v133, v3
	v_mul_f32_e32 v148, v133, v4
	v_mul_f32_e32 v149, v133, v5
	v_mul_f32_e32 v150, v133, v6
	v_mul_f32_e32 v151, v133, v7
	v_exp_f32_e32 v144, v144
	v_exp_f32_e32 v145, v145
	v_exp_f32_e32 v146, v146
	v_exp_f32_e32 v147, v147
	v_exp_f32_e32 v148, v148
	v_exp_f32_e32 v149, v149
	v_exp_f32_e32 v150, v150
	v_exp_f32_e32 v151, v151
	v_mul_f32_e32 v0, v0, v32
	v_mul_f32_e32 v1, v1, v33
	v_mul_f32_e32 v2, v2, v34
	v_mul_f32_e32 v3, v3, v35
	v_mul_f32_e32 v4, v4, v36
	v_mul_f32_e32 v5, v5, v37
	v_mul_f32_e32 v6, v6, v38
	v_mul_f32_e32 v7, v7, v39
	v_add_f32_e32 v144, 1.0, v144
	v_add_f32_e32 v145, 1.0, v145
	v_add_f32_e32 v146, 1.0, v146
	v_add_f32_e32 v147, 1.0, v147
	v_add_f32_e32 v148, 1.0, v148
	v_add_f32_e32 v149, 1.0, v149
	v_add_f32_e32 v150, 1.0, v150
	v_add_f32_e32 v151, 1.0, v151
	v_rcp_f32_e32 v144, v144
	v_rcp_f32_e32 v145, v145
	v_rcp_f32_e32 v146, v146
	v_rcp_f32_e32 v147, v147
	v_rcp_f32_e32 v148, v148
	v_rcp_f32_e32 v149, v149
	v_rcp_f32_e32 v150, v150
	v_rcp_f32_e32 v151, v151
	v_mul_f32_e32 v0, v0, v131
	v_mul_f32_e32 v1, v1, v131
	v_mul_f32_e32 v2, v2, v131
	v_mul_f32_e32 v3, v3, v131
	v_mul_f32_e32 v4, v4, v131
	v_mul_f32_e32 v5, v5, v131
	v_mul_f32_e32 v6, v6, v131
	v_mul_f32_e32 v7, v7, v131
	v_mul_f32_e32 v0, v0, v144
	v_mul_f32_e32 v1, v1, v145
	v_mul_f32_e32 v2, v2, v146
	v_mul_f32_e32 v3, v3, v147
	v_mul_f32_e32 v4, v4, v148
	v_mul_f32_e32 v5, v5, v149
	v_mul_f32_e32 v6, v6, v150
	v_mul_f32_e32 v7, v7, v151
	v_cvt_pk_bf16_f32 v152, v0, v1
	v_cvt_pk_bf16_f32 v153, v2, v3
	v_cvt_pk_bf16_f32 v154, v4, v5
	v_cvt_pk_bf16_f32 v155, v6, v7
	s_nop 1
	global_store_dwordx4 v132, v[152:155], s[50:51] nt
	s_nop 1
	v_fmamk_f32 v131, v135, 0x3a000000, v130
	v_add_u32_e32 v132, 0x2c000, v129
	v_rsq_f32_e32 v131, v131
	s_nop 0
	v_mul_f32_e32 v133, 0xbfb8aa3b, v131
	v_mul_f32_e32 v131, v131, v131
	v_mul_f32_e32 v144, v133, v8
	v_mul_f32_e32 v145, v133, v9
	v_mul_f32_e32 v146, v133, v10
	v_mul_f32_e32 v147, v133, v11
	v_mul_f32_e32 v148, v133, v12
	v_mul_f32_e32 v149, v133, v13
	v_mul_f32_e32 v150, v133, v14
	v_mul_f32_e32 v151, v133, v15
	v_exp_f32_e32 v144, v144
	v_exp_f32_e32 v145, v145
	v_exp_f32_e32 v146, v146
	v_exp_f32_e32 v147, v147
	v_exp_f32_e32 v148, v148
	v_exp_f32_e32 v149, v149
	v_exp_f32_e32 v150, v150
	v_exp_f32_e32 v151, v151
	v_mul_f32_e32 v8, v8, v40
	v_mul_f32_e32 v9, v9, v41
	v_mul_f32_e32 v10, v10, v42
	v_mul_f32_e32 v11, v11, v43
	v_mul_f32_e32 v12, v12, v44
	v_mul_f32_e32 v13, v13, v45
	v_mul_f32_e32 v14, v14, v46
	v_mul_f32_e32 v15, v15, v47
	v_add_f32_e32 v144, 1.0, v144
	v_add_f32_e32 v145, 1.0, v145
	v_add_f32_e32 v146, 1.0, v146
	v_add_f32_e32 v147, 1.0, v147
	v_add_f32_e32 v148, 1.0, v148
	v_add_f32_e32 v149, 1.0, v149
	v_add_f32_e32 v150, 1.0, v150
	v_add_f32_e32 v151, 1.0, v151
	v_rcp_f32_e32 v144, v144
	v_rcp_f32_e32 v145, v145
	v_rcp_f32_e32 v146, v146
	v_rcp_f32_e32 v147, v147
	v_rcp_f32_e32 v148, v148
	v_rcp_f32_e32 v149, v149
	v_rcp_f32_e32 v150, v150
	v_rcp_f32_e32 v151, v151
	v_mul_f32_e32 v8, v8, v131
	v_mul_f32_e32 v9, v9, v131
	v_mul_f32_e32 v10, v10, v131
	v_mul_f32_e32 v11, v11, v131
	v_mul_f32_e32 v12, v12, v131
	v_mul_f32_e32 v13, v13, v131
	v_mul_f32_e32 v14, v14, v131
	v_mul_f32_e32 v15, v15, v131
	v_mul_f32_e32 v8, v8, v144
	v_mul_f32_e32 v9, v9, v145
	v_mul_f32_e32 v10, v10, v146
	v_mul_f32_e32 v11, v11, v147
	v_mul_f32_e32 v12, v12, v148
	v_mul_f32_e32 v13, v13, v149
	v_mul_f32_e32 v14, v14, v150
	v_mul_f32_e32 v15, v15, v151
	v_cvt_pk_bf16_f32 v152, v8, v9
	v_cvt_pk_bf16_f32 v153, v10, v11
	v_cvt_pk_bf16_f32 v154, v12, v13
	v_cvt_pk_bf16_f32 v155, v14, v15
	s_nop 1
	global_store_dwordx4 v132, v[152:155], s[50:51] nt
	s_nop 1
	v_fmamk_f32 v131, v136, 0x3a000000, v130
	v_add_u32_e32 v132, 0x58000, v129
	v_rsq_f32_e32 v131, v131
	s_nop 0
	v_mul_f32_e32 v133, 0xbfb8aa3b, v131
	v_mul_f32_e32 v131, v131, v131
	v_mul_f32_e32 v144, v133, v16
	v_mul_f32_e32 v145, v133, v17
	v_mul_f32_e32 v146, v133, v18
	v_mul_f32_e32 v147, v133, v19
	v_mul_f32_e32 v148, v133, v20
	v_mul_f32_e32 v149, v133, v21
	v_mul_f32_e32 v150, v133, v22
	v_mul_f32_e32 v151, v133, v23
	v_exp_f32_e32 v144, v144
	v_exp_f32_e32 v145, v145
	v_exp_f32_e32 v146, v146
	v_exp_f32_e32 v147, v147
	v_exp_f32_e32 v148, v148
	v_exp_f32_e32 v149, v149
	v_exp_f32_e32 v150, v150
	v_exp_f32_e32 v151, v151
	v_mul_f32_e32 v16, v16, v48
	v_mul_f32_e32 v17, v17, v49
	v_mul_f32_e32 v18, v18, v50
	v_mul_f32_e32 v19, v19, v51
; __device__ __forceinline__ unsigned cvt_pk_bf16(float lo, float hi) { unsigned r; asm volatile("v_cvt_pk_bf16_f32 %0, %1, %2" : "=v"(r) : "v"(lo), "v"(hi)); return r; }
;     __device__ __forceinline__ void operator()(const f32x4 (&acc)[2][2][4][2], const Unit& u, int wr, int wc, int fr, int fq) const {
;     ...
;             for (int m = 0; m < 4; ++m) { const int row = row0 + ai * HALF + m * 16; const float rs = __builtin_amdgcn_rsqf(rsv[ai][m] * inv_n + eps);
;                 float a[8];
; #pragma unroll
;                 for (int n = 0; n < 2; ++n)
; #pragma unroll
;                     for (int i = 0; i < 4; ++i) { const float g = acc[ai][0][m][n][i] * rs, up = acc[ai][1][m][n][i] * rs;
;                         a[n * 4 + i] = g * __builtin_amdgcn_rcpf(1.0f + __builtin_amdgcn_exp2f(-1.4426950408889634f * g)) * up; }
;                 u32x4 w; w.x = cvt_pk_bf16(a[0], a[1]); w.y = cvt_pk_bf16(a[2], a[3]); w.z = cvt_pk_bf16(a[4], a[5]); w.w = cvt_pk_bf16(a[6], a[7]);
;                 *(u32x4*)(O + (size_t)row * ldc + col0) = w; }
	v_mul_f32_e32 v20, v20, v52
	v_mul_f32_e32 v21, v21, v53
	v_mul_f32_e32 v22, v22, v54
	v_mul_f32_e32 v23, v23, v55
	v_add_f32_e32 v144, 1.0, v144
	v_add_f32_e32 v145, 1.0, v145
	v_add_f32_e32 v146, 1.0, v146
	v_add_f32_e32 v147, 1.0, v147
	v_add_f32_e32 v148, 1.0, v148
	v_add_f32_e32 v149, 1.0, v149
	v_add_f32_e32 v150, 1.0, v150
	v_add_f32_e32 v151, 1.0, v151
	v_rcp_f32_e32 v144, v144
	v_rcp_f32_e32 v145, v145
	v_rcp_f32_e32 v146, v146
	v_rcp_f32_e32 v147, v147
	v_rcp_f32_e32 v148, v148
	v_rcp_f32_e32 v149, v149
	v_rcp_f32_e32 v150, v150
	v_rcp_f32_e32 v151, v151
	v_mul_f32_e32 v16, v16, v131
	v_mul_f32_e32 v17, v17, v131
	v_mul_f32_e32 v18, v18, v131
	v_mul_f32_e32 v19, v19, v131
	v_mul_f32_e32 v20, v20, v131
	v_mul_f32_e32 v21, v21, v131
	v_mul_f32_e32 v22, v22, v131
	v_mul_f32_e32 v23, v23, v131
	v_mul_f32_e32 v16, v16, v144
	v_mul_f32_e32 v17, v17, v145
	v_mul_f32_e32 v18, v18, v146
	v_mul_f32_e32 v19, v19, v147
	v_mul_f32_e32 v20, v20, v148
	v_mul_f32_e32 v21, v21, v149
	v_mul_f32_e32 v22, v22, v150
	v_mul_f32_e32 v23, v23, v151
	v_cvt_pk_bf16_f32 v152, v16, v17
	v_cvt_pk_bf16_f32 v153, v18, v19
	v_cvt_pk_bf16_f32 v154, v20, v21
	v_cvt_pk_bf16_f32 v155, v22, v23
	s_nop 1
	global_store_dwordx4 v132, v[152:155], s[50:51] nt
	s_nop 1
	v_fmamk_f32 v131, v137, 0x3a000000, v130
	v_add_u32_e32 v132, 0x84000, v129
	v_rsq_f32_e32 v131, v131
	s_nop 0
	v_mul_f32_e32 v133, 0xbfb8aa3b, v131
	v_mul_f32_e32 v131, v131, v131
	v_mul_f32_e32 v144, v133, v24
	v_mul_f32_e32 v145, v133, v25
	v_mul_f32_e32 v146, v133, v26
	v_mul_f32_e32 v147, v133, v27
	v_mul_f32_e32 v148, v133, v28
	v_mul_f32_e32 v149, v133, v29
	v_mul_f32_e32 v150, v133, v30
	v_mul_f32_e32 v151, v133, v31
	v_exp_f32_e32 v144, v144
	v_exp_f32_e32 v145, v145
	v_exp_f32_e32 v146, v146
	v_exp_f32_e32 v147, v147
	v_exp_f32_e32 v148, v148
	v_exp_f32_e32 v149, v149
	v_exp_f32_e32 v150, v150
	v_exp_f32_e32 v151, v151
	v_mul_f32_e32 v24, v24, v56
	v_mul_f32_e32 v25, v25, v57
	v_mul_f32_e32 v26, v26, v58
	v_mul_f32_e32 v27, v27, v59
	v_mul_f32_e32 v28, v28, v60
	v_mul_f32_e32 v29, v29, v61
	v_mul_f32_e32 v30, v30, v62
	v_mul_f32_e32 v31, v31, v63
	v_add_f32_e32 v144, 1.0, v144
	v_add_f32_e32 v145, 1.0, v145
	v_add_f32_e32 v146, 1.0, v146
	v_add_f32_e32 v147, 1.0, v147
	v_add_f32_e32 v148, 1.0, v148
	v_add_f32_e32 v149, 1.0, v149
	v_add_f32_e32 v150, 1.0, v150
	v_add_f32_e32 v151, 1.0, v151
	v_rcp_f32_e32 v144, v144
	v_rcp_f32_e32 v145, v145
	v_rcp_f32_e32 v146, v146
	v_rcp_f32_e32 v147, v147
	v_rcp_f32_e32 v148, v148
	v_rcp_f32_e32 v149, v149
	v_rcp_f32_e32 v150, v150
	v_rcp_f32_e32 v151, v151
	v_mul_f32_e32 v24, v24, v131
	v_mul_f32_e32 v25, v25, v131
	v_mul_f32_e32 v26, v26, v131
	v_mul_f32_e32 v27, v27, v131
	v_mul_f32_e32 v28, v28, v131
	v_mul_f32_e32 v29, v29, v131
	v_mul_f32_e32 v30, v30, v131
	v_mul_f32_e32 v31, v31, v131
	v_mul_f32_e32 v24, v24, v144
	v_mul_f32_e32 v25, v25, v145
	v_mul_f32_e32 v26, v26, v146
	v_mul_f32_e32 v27, v27, v147
	v_mul_f32_e32 v28, v28, v148
	v_mul_f32_e32 v29, v29, v149
	v_mul_f32_e32 v30, v30, v150
	v_mul_f32_e32 v31, v31, v151
	v_cvt_pk_bf16_f32 v152, v24, v25
	v_cvt_pk_bf16_f32 v153, v26, v27
	v_cvt_pk_bf16_f32 v154, v28, v29
	v_cvt_pk_bf16_f32 v155, v30, v31
	s_nop 1
	global_store_dwordx4 v132, v[152:155], s[50:51] nt
	s_nop 1
	s_waitcnt vmcnt(4)
	v_fmamk_f32 v131, v138, 0x3a000000, v130
	v_add_u32_e32 v132, 0x160000, v129
	v_rsq_f32_e32 v131, v131
	s_nop 0
	v_mul_f32_e32 v133, 0xbfb8aa3b, v131
	v_mul_f32_e32 v131, v131, v131
	v_mul_f32_e32 v144, v133, v64
	v_mul_f32_e32 v145, v133, v65
	v_mul_f32_e32 v146, v133, v66
	v_mul_f32_e32 v147, v133, v67
	v_mul_f32_e32 v148, v133, v68
	v_mul_f32_e32 v149, v133, v69
	v_mul_f32_e32 v150, v133, v70
	v_mul_f32_e32 v151, v133, v71
	v_exp_f32_e32 v144, v144
	v_exp_f32_e32 v145, v145
	v_exp_f32_e32 v146, v146
	v_exp_f32_e32 v147, v147
	v_exp_f32_e32 v148, v148
	v_exp_f32_e32 v149, v149
	v_exp_f32_e32 v150, v150
	v_exp_f32_e32 v151, v151
	v_mul_f32_e32 v64, v64, v96
	v_mul_f32_e32 v65, v65, v97
	v_mul_f32_e32 v66, v66, v98
	v_mul_f32_e32 v67, v67, v99
	v_mul_f32_e32 v68, v68, v100
	v_mul_f32_e32 v69, v69, v101
	v_mul_f32_e32 v70, v70, v102
	v_mul_f32_e32 v71, v71, v103
	v_add_f32_e32 v144, 1.0, v144
	v_add_f32_e32 v145, 1.0, v145
	v_add_f32_e32 v146, 1.0, v146
	v_add_f32_e32 v147, 1.0, v147
	v_add_f32_e32 v148, 1.0, v148
	v_add_f32_e32 v149, 1.0, v149
	v_add_f32_e32 v150, 1.0, v150
	v_add_f32_e32 v151, 1.0, v151
	v_rcp_f32_e32 v144, v144
	v_rcp_f32_e32 v145, v145
	v_rcp_f32_e32 v146, v146
	v_rcp_f32_e32 v147, v147
	v_rcp_f32_e32 v148, v148
	v_rcp_f32_e32 v149, v149
	v_rcp_f32_e32 v150, v150
	v_rcp_f32_e32 v151, v151
	v_mul_f32_e32 v64, v64, v131
	v_mul_f32_e32 v65, v65, v131
	v_mul_f32_e32 v66, v66, v131
	v_mul_f32_e32 v67, v67, v131
	v_mul_f32_e32 v68, v68, v131
	v_mul_f32_e32 v69, v69, v131
	v_mul_f32_e32 v70, v70, v131
	v_mul_f32_e32 v71, v71, v131
	v_mul_f32_e32 v64, v64, v144
	v_mul_f32_e32 v65, v65, v145
	v_mul_f32_e32 v66, v66, v146
	v_mul_f32_e32 v67, v67, v147
	v_mul_f32_e32 v68, v68, v148
	v_mul_f32_e32 v69, v69, v149
	v_mul_f32_e32 v70, v70, v150
	v_mul_f32_e32 v71, v71, v151
	v_cvt_pk_bf16_f32 v152, v64, v65
	v_cvt_pk_bf16_f32 v153, v66, v67
	v_cvt_pk_bf16_f32 v154, v68, v69
	v_cvt_pk_bf16_f32 v155, v70, v71
	s_nop 1
	global_store_dwordx4 v132, v[152:155], s[50:51] nt
	s_nop 1
	v_fmamk_f32 v131, v139, 0x3a000000, v130
	v_add_u32_e32 v132, 0x18c000, v129
	v_rsq_f32_e32 v131, v131
	s_nop 0
	v_mul_f32_e32 v133, 0xbfb8aa3b, v131
	v_mul_f32_e32 v131, v131, v131
	v_mul_f32_e32 v144, v133, v72
	v_mul_f32_e32 v145, v133, v73
	v_mul_f32_e32 v146, v133, v74
	v_mul_f32_e32 v147, v133, v75
	v_mul_f32_e32 v148, v133, v76
; __device__ __forceinline__ unsigned cvt_pk_bf16(float lo, float hi) { unsigned r; asm volatile("v_cvt_pk_bf16_f32 %0, %1, %2" : "=v"(r) : "v"(lo), "v"(hi)); return r; }
;     __device__ __forceinline__ void operator()(const f32x4 (&acc)[2][2][4][2], const Unit& u, int wr, int wc, int fr, int fq) const {
;     ...
;             for (int m = 0; m < 4; ++m) { const int row = row0 + ai * HALF + m * 16; const float rs = __builtin_amdgcn_rsqf(rsv[ai][m] * inv_n + eps);
;                 float a[8];
; #pragma unroll
;                 for (int n = 0; n < 2; ++n)
; #pragma unroll
;                     for (int i = 0; i < 4; ++i) { const float g = acc[ai][0][m][n][i] * rs, up = acc[ai][1][m][n][i] * rs;
;                         a[n * 4 + i] = g * __builtin_amdgcn_rcpf(1.0f + __builtin_amdgcn_exp2f(-1.4426950408889634f * g)) * up; }
;                 u32x4 w; w.x = cvt_pk_bf16(a[0], a[1]); w.y = cvt_pk_bf16(a[2], a[3]); w.z = cvt_pk_bf16(a[4], a[5]); w.w = cvt_pk_bf16(a[6], a[7]);
;                 *(u32x4*)(O + (size_t)row * ldc + col0) = w; }
; template <class Epi, class Sched, bool ALIGN_EPI = false, bool SP2 = false>
; __device__ __forceinline__ void gemm_phase(PG8_LAS unsigned char* lds, const Gemm g, const Sched& S, const Epi& E) {
;     ...
;         if (!has_next) break;
; #pragma unroll
;         for (int a = 0; a < 2; ++a)
; #pragma unroll
;             for (int b = 0; b < 2; ++b)
; #pragma unroll
;                 for (int m = 0; m < 4; ++m)
; #pragma unroll
;                     for (int n = 0; n < 2; ++n) acc[a][b][m][n] = (f32x4){0.f, 0.f, 0.f, 0.f};
;         cur = nxt; cA = nA; cB = nB; ++ui;
	v_mul_f32_e32 v149, v133, v77
	v_mul_f32_e32 v150, v133, v78
	v_mul_f32_e32 v151, v133, v79
	v_exp_f32_e32 v144, v144
	v_exp_f32_e32 v145, v145
	v_exp_f32_e32 v146, v146
	v_exp_f32_e32 v147, v147
	v_exp_f32_e32 v148, v148
	v_exp_f32_e32 v149, v149
	v_exp_f32_e32 v150, v150
	v_exp_f32_e32 v151, v151
	v_mul_f32_e32 v72, v72, v104
	v_mul_f32_e32 v73, v73, v105
	v_mul_f32_e32 v74, v74, v106
	v_mul_f32_e32 v75, v75, v107
	v_mul_f32_e32 v76, v76, v108
	v_mul_f32_e32 v77, v77, v109
	v_mul_f32_e32 v78, v78, v110
	v_mul_f32_e32 v79, v79, v111
	v_add_f32_e32 v144, 1.0, v144
	v_add_f32_e32 v145, 1.0, v145
	v_add_f32_e32 v146, 1.0, v146
	v_add_f32_e32 v147, 1.0, v147
	v_add_f32_e32 v148, 1.0, v148
	v_add_f32_e32 v149, 1.0, v149
	v_add_f32_e32 v150, 1.0, v150
	v_add_f32_e32 v151, 1.0, v151
	v_rcp_f32_e32 v144, v144
	v_rcp_f32_e32 v145, v145
	v_rcp_f32_e32 v146, v146
	v_rcp_f32_e32 v147, v147
	v_rcp_f32_e32 v148, v148
	v_rcp_f32_e32 v149, v149
	v_rcp_f32_e32 v150, v150
	v_rcp_f32_e32 v151, v151
	v_mul_f32_e32 v72, v72, v131
	v_mul_f32_e32 v73, v73, v131
	v_mul_f32_e32 v74, v74, v131
	v_mul_f32_e32 v75, v75, v131
	v_mul_f32_e32 v76, v76, v131
	v_mul_f32_e32 v77, v77, v131
	v_mul_f32_e32 v78, v78, v131
	v_mul_f32_e32 v79, v79, v131
	v_mul_f32_e32 v72, v72, v144
	v_mul_f32_e32 v73, v73, v145
	v_mul_f32_e32 v74, v74, v146
	v_mul_f32_e32 v75, v75, v147
	v_mul_f32_e32 v76, v76, v148
	v_mul_f32_e32 v77, v77, v149
	v_mul_f32_e32 v78, v78, v150
	v_mul_f32_e32 v79, v79, v151
	v_cvt_pk_bf16_f32 v152, v72, v73
	v_cvt_pk_bf16_f32 v153, v74, v75
	v_cvt_pk_bf16_f32 v154, v76, v77
	v_cvt_pk_bf16_f32 v155, v78, v79
	s_nop 1
	global_store_dwordx4 v132, v[152:155], s[50:51] nt
	s_nop 1
	v_fmamk_f32 v131, v140, 0x3a000000, v130
	v_add_u32_e32 v132, 0x1b8000, v129
	v_rsq_f32_e32 v131, v131
	s_nop 0
	v_mul_f32_e32 v133, 0xbfb8aa3b, v131
	v_mul_f32_e32 v131, v131, v131
	v_mul_f32_e32 v144, v133, v80
	v_mul_f32_e32 v145, v133, v81
	v_mul_f32_e32 v146, v133, v82
	v_mul_f32_e32 v147, v133, v83
	v_mul_f32_e32 v148, v133, v84
	v_mul_f32_e32 v149, v133, v85
	v_mul_f32_e32 v150, v133, v86
	v_mul_f32_e32 v151, v133, v87
	v_exp_f32_e32 v144, v144
	v_exp_f32_e32 v145, v145
	v_exp_f32_e32 v146, v146
	v_exp_f32_e32 v147, v147
	v_exp_f32_e32 v148, v148
	v_exp_f32_e32 v149, v149
	v_exp_f32_e32 v150, v150
	v_exp_f32_e32 v151, v151
	v_mul_f32_e32 v80, v80, v112
	v_mul_f32_e32 v81, v81, v113
	v_mul_f32_e32 v82, v82, v114
	v_mul_f32_e32 v83, v83, v115
	v_mul_f32_e32 v84, v84, v116
	v_mul_f32_e32 v85, v85, v117
	v_mul_f32_e32 v86, v86, v118
	v_mul_f32_e32 v87, v87, v119
	v_add_f32_e32 v144, 1.0, v144
	v_add_f32_e32 v145, 1.0, v145
	v_add_f32_e32 v146, 1.0, v146
	v_add_f32_e32 v147, 1.0, v147
	v_add_f32_e32 v148, 1.0, v148
	v_add_f32_e32 v149, 1.0, v149
	v_add_f32_e32 v150, 1.0, v150
	v_add_f32_e32 v151, 1.0, v151
	v_rcp_f32_e32 v144, v144
	v_rcp_f32_e32 v145, v145
	v_rcp_f32_e32 v146, v146
	v_rcp_f32_e32 v147, v147
	v_rcp_f32_e32 v148, v148
	v_rcp_f32_e32 v149, v149
	v_rcp_f32_e32 v150, v150
	v_rcp_f32_e32 v151, v151
	v_mul_f32_e32 v80, v80, v131
	v_mul_f32_e32 v81, v81, v131
	v_mul_f32_e32 v82, v82, v131
	v_mul_f32_e32 v83, v83, v131
	v_mul_f32_e32 v84, v84, v131
	v_mul_f32_e32 v85, v85, v131
	v_mul_f32_e32 v86, v86, v131
	v_mul_f32_e32 v87, v87, v131
	v_mul_f32_e32 v80, v80, v144
	v_mul_f32_e32 v81, v81, v145
	v_mul_f32_e32 v82, v82, v146
	v_mul_f32_e32 v83, v83, v147
	v_mul_f32_e32 v84, v84, v148
	v_mul_f32_e32 v85, v85, v149
	v_mul_f32_e32 v86, v86, v150
	v_mul_f32_e32 v87, v87, v151
	v_cvt_pk_bf16_f32 v152, v80, v81
	v_cvt_pk_bf16_f32 v153, v82, v83
	v_cvt_pk_bf16_f32 v154, v84, v85
	v_cvt_pk_bf16_f32 v155, v86, v87
	s_nop 1
	global_store_dwordx4 v132, v[152:155], s[50:51] nt
	s_nop 1
	v_fmamk_f32 v131, v141, 0x3a000000, v130
	v_add_u32_e32 v132, 0x1e4000, v129
	v_rsq_f32_e32 v131, v131
	s_nop 0
	v_mul_f32_e32 v133, 0xbfb8aa3b, v131
	v_mul_f32_e32 v131, v131, v131
	v_mul_f32_e32 v144, v133, v88
	v_mul_f32_e32 v145, v133, v89
	v_mul_f32_e32 v146, v133, v90
	v_mul_f32_e32 v147, v133, v91
	v_mul_f32_e32 v148, v133, v92
	v_mul_f32_e32 v149, v133, v93
	v_mul_f32_e32 v150, v133, v94
	v_mul_f32_e32 v151, v133, v95
	v_exp_f32_e32 v144, v144
	v_exp_f32_e32 v145, v145
	v_exp_f32_e32 v146, v146
	v_exp_f32_e32 v147, v147
	v_exp_f32_e32 v148, v148
	v_exp_f32_e32 v149, v149
	v_exp_f32_e32 v150, v150
	v_exp_f32_e32 v151, v151
	v_mul_f32_e32 v88, v88, v120
	v_mul_f32_e32 v89, v89, v121
	v_mul_f32_e32 v90, v90, v122
	v_mul_f32_e32 v91, v91, v123
	v_mul_f32_e32 v92, v92, v124
	v_mul_f32_e32 v93, v93, v125
	v_mul_f32_e32 v94, v94, v126
	v_mul_f32_e32 v95, v95, v127
	v_add_f32_e32 v144, 1.0, v144
	v_add_f32_e32 v145, 1.0, v145
	v_add_f32_e32 v146, 1.0, v146
	v_add_f32_e32 v147, 1.0, v147
	v_add_f32_e32 v148, 1.0, v148
	v_add_f32_e32 v149, 1.0, v149
	v_add_f32_e32 v150, 1.0, v150
	v_add_f32_e32 v151, 1.0, v151
	v_rcp_f32_e32 v144, v144
	v_rcp_f32_e32 v145, v145
	v_rcp_f32_e32 v146, v146
	v_rcp_f32_e32 v147, v147
	v_rcp_f32_e32 v148, v148
	v_rcp_f32_e32 v149, v149
	v_rcp_f32_e32 v150, v150
	v_rcp_f32_e32 v151, v151
	v_mul_f32_e32 v88, v88, v131
	v_mul_f32_e32 v89, v89, v131
	v_mul_f32_e32 v90, v90, v131
	v_mul_f32_e32 v91, v91, v131
	v_mul_f32_e32 v92, v92, v131
	v_mul_f32_e32 v93, v93, v131
	v_mul_f32_e32 v94, v94, v131
	v_mul_f32_e32 v95, v95, v131
	v_mul_f32_e32 v88, v88, v144
	v_mul_f32_e32 v89, v89, v145
	v_mul_f32_e32 v90, v90, v146
	v_mul_f32_e32 v91, v91, v147
	v_mul_f32_e32 v92, v92, v148
	v_mul_f32_e32 v93, v93, v149
	v_mul_f32_e32 v94, v94, v150
	v_mul_f32_e32 v95, v95, v151
	v_cvt_pk_bf16_f32 v152, v88, v89
	v_cvt_pk_bf16_f32 v153, v90, v91
	v_cvt_pk_bf16_f32 v154, v92, v93
	v_cvt_pk_bf16_f32 v155, v94, v95
	s_nop 1
	global_store_dwordx4 v132, v[152:155], s[50:51] nt
	s_nop 1
	s_cmp_eq_u32 s19, 0
	s_cbranch_scc1 .Lp5_done
	s_mov_b32 s17, s20
	s_mov_b32 s18, s21
	s_mov_b64 s[22:23], s[26:27]
	s_mov_b64 s[24:25], s[28:29]
	s_add_u32 s16, s16, 1
	s_branch .Lp5_unit
